# P4 attention: K/V tile staging two tiles ahead (two register sets by parity), mask-free softmax fast paths for fully valid far tiles
# speedup vs baseline: 1.0112x; 1.0024x over previous
.LBB0_1162:
	s_or_b64 exec, exec, s[18:19]
	s_add_i32 s18, s31, 0x7ff
	s_addk_i32 s31, 0x501
	s_ashr_i32 s18, s18, 5
	s_max_i32 s20, s31, 0
	s_and_b32 s35, s18, -2
	s_lshr_b32 s36, s20, 5
	s_add_i32 s19, s35, 2
	s_sub_i32 s20, s18, s36
	s_add_i32 s31, s20, s19
	s_lshl_b64 s[22:23], s[2:3], 19
	s_add_u32 s3, s14, s22
	s_addc_u32 s14, s15, s23
	s_add_u32 s20, s3, 0x39800000
	s_addc_u32 s21, s14, 0
	s_add_u32 s3, s16, s22
	s_addc_u32 s14, s17, s23
	s_add_u32 s16, s3, 0x3be00000
	v_lshlrev_b32_e32 v64, 4, v165
	v_readlane_b32 s3, v252, 36
	s_waitcnt lgkmcnt(0)
	s_addc_u32 s17, s14, 0
	s_add_i32 s22, s31, 1
	v_add_u32_e32 v217, s3, v64
	ds_read_b128 v[64:67], v217
	ds_read_b128 v[68:71], v217 offset:32
	ds_read_b128 v[72:75], v217 offset:64
	ds_read_b128 v[76:79], v217 offset:96
	v_readlane_b32 s3, v252, 58
	s_waitcnt lgkmcnt(3)
	v_mul_f32_e32 v48, v48, v64
	v_mul_f32_e32 v49, v49, v65
	v_lshl_add_u32 v218, v216, 2, s3
	v_cvt_pk_bf16_f32 v48, v48, v49
	ds_write_b32 v218, v48 offset:32768
	v_mul_f32_e32 v48, v50, v66
	v_mul_f32_e32 v49, v51, v67
	v_cvt_pk_bf16_f32 v48, v48, v49
	ds_write_b32 v218, v48 offset:33024
	s_waitcnt lgkmcnt(4)
	v_mul_f32_e32 v48, v52, v68
	v_mul_f32_e32 v49, v53, v69
	v_cvt_pk_bf16_f32 v48, v48, v49
	ds_write_b32 v218, v48 offset:33280
	v_mul_f32_e32 v48, v54, v70
	v_mul_f32_e32 v49, v55, v71
	v_cvt_pk_bf16_f32 v48, v48, v49
	ds_write_b32 v218, v48 offset:33536
	s_waitcnt lgkmcnt(5)
	v_mul_f32_e32 v48, v56, v72
	v_mul_f32_e32 v49, v57, v73
	v_cvt_pk_bf16_f32 v48, v48, v49
	ds_write_b32 v218, v48 offset:33792
	v_mul_f32_e32 v48, v58, v74
	v_mul_f32_e32 v49, v59, v75
	v_cvt_pk_bf16_f32 v48, v48, v49
	ds_write_b32 v218, v48 offset:34048
	s_waitcnt lgkmcnt(6)
	v_mul_f32_e32 v48, v60, v76
	v_mul_f32_e32 v49, v61, v77
	v_cvt_pk_bf16_f32 v48, v48, v49
	ds_write_b32 v218, v48 offset:34304
	v_mul_f32_e32 v48, v62, v78
	v_mul_f32_e32 v32, v32, v64
	v_mul_f32_e32 v49, v63, v79
	v_cvt_pk_bf16_f32 v48, v48, v49
	ds_write_b32 v218, v48 offset:34560
	v_mul_f32_e32 v33, v33, v65
	v_cvt_pk_bf16_f32 v32, v32, v33
	ds_write_b32 v218, v32 offset:34816
	v_mul_f32_e32 v32, v34, v66
	v_mul_f32_e32 v33, v35, v67
	v_cvt_pk_bf16_f32 v32, v32, v33
	ds_write_b32 v218, v32 offset:35072
	v_mul_f32_e32 v32, v36, v68
	v_mul_f32_e32 v33, v37, v69
	v_cvt_pk_bf16_f32 v32, v32, v33
	ds_write_b32 v218, v32 offset:35328
	v_mul_f32_e32 v32, v38, v70
	v_mul_f32_e32 v33, v39, v71
	v_cvt_pk_bf16_f32 v32, v32, v33
	ds_write_b32 v218, v32 offset:35584
	v_mul_f32_e32 v32, v40, v72
	v_mul_f32_e32 v33, v41, v73
	v_cvt_pk_bf16_f32 v32, v32, v33
	ds_write_b32 v218, v32 offset:35840
	v_mul_f32_e32 v32, v42, v74
	v_mul_f32_e32 v33, v43, v75
	v_cvt_pk_bf16_f32 v32, v32, v33
	ds_write_b32 v218, v32 offset:36096
	v_mul_f32_e32 v32, v44, v76
	v_mul_f32_e32 v33, v45, v77
	v_cvt_pk_bf16_f32 v32, v32, v33
	ds_write_b32 v218, v32 offset:36352
	v_mul_f32_e32 v32, v46, v78
	v_mul_f32_e32 v16, v16, v64
	v_mul_f32_e32 v33, v47, v79
	v_cvt_pk_bf16_f32 v32, v32, v33
	ds_write_b32 v218, v32 offset:36608
	v_mul_f32_e32 v17, v17, v65
	v_cvt_pk_bf16_f32 v16, v16, v17
	ds_write_b32 v218, v16 offset:36864
	v_mul_f32_e32 v16, v18, v66
	v_mul_f32_e32 v17, v19, v67
	v_cvt_pk_bf16_f32 v16, v16, v17
	ds_write_b32 v218, v16 offset:37120
	v_mul_f32_e32 v16, v20, v68
	v_mul_f32_e32 v17, v21, v69
	v_cvt_pk_bf16_f32 v16, v16, v17
	ds_write_b32 v218, v16 offset:37376
	v_mul_f32_e32 v16, v22, v70
	v_mul_f32_e32 v17, v23, v71
	v_cvt_pk_bf16_f32 v16, v16, v17
	ds_write_b32 v218, v16 offset:37632
	v_mul_f32_e32 v16, v24, v72
	v_mul_f32_e32 v17, v25, v73
	v_cvt_pk_bf16_f32 v16, v16, v17
	ds_write_b32 v218, v16 offset:37888
	v_mul_f32_e32 v16, v26, v74
	v_mul_f32_e32 v17, v27, v75
	v_cvt_pk_bf16_f32 v16, v16, v17
	ds_write_b32 v218, v16 offset:38144
	v_mul_f32_e32 v16, v28, v76
	v_mul_f32_e32 v17, v29, v77
	v_cvt_pk_bf16_f32 v16, v16, v17
	ds_write_b32 v218, v16 offset:38400
	v_mul_f32_e32 v16, v30, v78
	v_mul_f32_e32 v0, v0, v64
	v_mul_f32_e32 v17, v31, v79
	v_cvt_pk_bf16_f32 v16, v16, v17
	ds_write_b32 v218, v16 offset:38656
	v_mul_f32_e32 v1, v1, v65
	v_cvt_pk_bf16_f32 v0, v0, v1
	ds_write_b32 v218, v0 offset:38912
	v_mul_f32_e32 v0, v2, v66
	v_mul_f32_e32 v1, v3, v67
	v_cvt_pk_bf16_f32 v0, v0, v1
	ds_write_b32 v218, v0 offset:39168
	v_mul_f32_e32 v0, v4, v68
	v_mul_f32_e32 v1, v5, v69
	v_cvt_pk_bf16_f32 v0, v0, v1
	ds_write_b32 v218, v0 offset:39424
	v_mul_f32_e32 v0, v6, v70
	v_mul_f32_e32 v1, v7, v71
	v_cvt_pk_bf16_f32 v0, v0, v1
	ds_write_b32 v218, v0 offset:39680
	v_mul_f32_e32 v0, v8, v72
	v_mul_f32_e32 v1, v9, v73
	v_cvt_pk_bf16_f32 v0, v0, v1
	ds_write_b32 v218, v0 offset:39936
	v_mul_f32_e32 v0, v10, v74
	v_mul_f32_e32 v1, v11, v75
	v_cvt_pk_bf16_f32 v0, v0, v1
	ds_write_b32 v218, v0 offset:40192
	v_mul_f32_e32 v0, v12, v76
	v_mul_f32_e32 v1, v13, v77
	v_cvt_pk_bf16_f32 v0, v0, v1
	v_readlane_b32 s38, v254, 54
	v_lshlrev_b32_e32 v152, 3, v216
	ds_write_b32 v218, v0 offset:40448
	v_mul_f32_e32 v0, v14, v78
	v_readlane_b32 s39, v254, 55
	s_add_u32 s14, s20, s38
	v_mul_f32_e32 v1, v15, v79
	v_cvt_pk_bf16_f32 v0, v0, v1
	s_addc_u32 s15, s21, s39
	v_lshlrev_b64 v[170:171], 1, v[152:153]
	ds_write_b32 v218, v0 offset:40704
	v_lshl_add_u64 v[0:1], s[14:15], 0, v[170:171]
	s_add_u32 s14, s16, s38
	s_addc_u32 s15, s17, s39
	v_lshl_add_u64 v[4:5], s[14:15], 0, v[170:171]
	s_waitcnt lgkmcnt(0)
	s_waitcnt lgkmcnt(0)
	s_barrier
	s_mov_b64 s[100:101], 0x2000
	v_lshl_add_u64 v[144:145], v[0:1], 0, s[100:101]
	v_lshl_add_u64 v[148:149], v[4:5], 0, s[100:101]
	global_load_dwordx4 v[0:3], v[0:1], off
	v_readlane_b32 s3, v252, 59
	global_load_dwordx4 v[4:7], v[4:5], off
	global_load_dwordx4 v[144:147], v[144:145], off
	global_load_dwordx4 v[148:151], v[148:149], off
	s_mov_b32 s23, 0
	v_lshl_add_u32 v219, v216, 4, s3
	s_cmp_lt_i32 s22, 1
	s_waitcnt vmcnt(3)
	ds_write_b128 v219, v[0:3]
	s_waitcnt vmcnt(2)
	ds_write_b128 v219, v[4:7] offset:16384
	s_cbranch_scc1 .LBB0_1192
	v_readlane_b32 s14, v254, 31
	s_and_b32 s2, s2, -2
	v_readlane_b32 s15, v254, 32
	s_or_b32 s2, s2, s30
	s_mov_b32 s3, s15
	s_add_i32 s14, s2, 32
	v_writelane_b32 v254, s2, 31
	v_add_f32_e32 v172, v172, v164
	v_mov_b32_e32 v205, 0
	v_writelane_b32 v254, s3, 32
	s_lshl_b64 s[2:3], s[14:15], 19
	s_add_u32 s10, s10, s2
	s_addc_u32 s11, s11, s3
	s_add_u32 s30, s10, 0x39800000
	s_addc_u32 s31, s11, 0
	s_add_u32 s2, s12, s2
	s_addc_u32 s3, s13, s3
	s_add_u32 s33, s2, 0x3be00000
	s_addc_u32 s34, s3, 0
	s_sub_i32 s35, s36, s35
	s_mov_b64 s[2:3], 0x3624
	s_add_i32 s35, s35, -2
	s_add_i32 s36, s27, 0xfffffe01
	s_or_b32 s37, s27, 31
	v_add_u32_e32 v220, -2, v162
	v_add_u32_e32 v221, -3, v162
	v_add_u32_e32 v222, -8, v162
	v_add_u32_e32 v223, -9, v162
	v_add_u32_e32 v224, -10, v162
	v_add_u32_e32 v225, -11, v162
	v_add_u32_e32 v226, -16, v162
	v_subrev_u32_e32 v227, 17, v162
	v_subrev_u32_e32 v228, 18, v162
	v_subrev_u32_e32 v229, 19, v162
	v_subrev_u32_e32 v230, 24, v162
	v_subrev_u32_e32 v231, 25, v162
	v_subrev_u32_e32 v232, 26, v162
	v_subrev_u32_e32 v233, 27, v162
	v_lshl_add_u64 v[174:175], v[168:169], 0, s[2:3]
	v_mov_b32_e32 v173, v172
	v_mov_b32_e32 v176, v172
	v_mov_b32_e32 v177, v172
	v_mov_b32_e32 v178, v172
	v_mov_b32_e32 v179, v172
	v_mov_b32_e32 v180, v172
	v_mov_b32_e32 v181, v172
	v_mov_b32_e32 v182, v172
	v_mov_b32_e32 v183, v172
	v_mov_b32_e32 v184, v172
	v_mov_b32_e32 v185, v172
	v_mov_b32_e32 v186, v172
	v_mov_b32_e32 v187, v172
	v_mov_b32_e32 v188, v172
	v_mov_b32_e32 v189, v172
	v_mov_b32_e32 v165, v164
	v_mov_b32_e32 v190, v164
	v_mov_b32_e32 v191, v164
	v_mov_b32_e32 v192, v164
	v_mov_b32_e32 v193, v164
	v_mov_b32_e32 v194, v164
	v_mov_b32_e32 v195, v164
	v_mov_b32_e32 v196, v164
	v_mov_b32_e32 v197, v164
	v_mov_b32_e32 v198, v164
	v_mov_b32_e32 v199, v164
	v_mov_b32_e32 v200, v164
	v_mov_b32_e32 v201, v164
	v_mov_b32_e32 v202, v164
	v_mov_b32_e32 v203, v164
	v_lshl_add_u32 v152, v152, 1, 0
	s_mov_b32 s39, 0
	v_mov_b32_e32 v48, v205
	v_mov_b32_e32 v49, v205
	v_mov_b32_e32 v50, v205
	v_mov_b32_e32 v51, v205
	v_mov_b32_e32 v52, v205
	v_mov_b32_e32 v53, v205
	v_mov_b32_e32 v54, v205
	v_mov_b32_e32 v55, v205
	v_mov_b32_e32 v56, v205
	v_mov_b32_e32 v57, v205
	v_mov_b32_e32 v58, v205
	v_mov_b32_e32 v59, v205
	v_mov_b32_e32 v60, v205
	v_mov_b32_e32 v61, v205
	v_mov_b32_e32 v62, v205
	v_mov_b32_e32 v63, v205
	v_mov_b32_e32 v32, v205
	v_mov_b32_e32 v33, v205
	v_mov_b32_e32 v34, v205
	v_mov_b32_e32 v35, v205
	v_mov_b32_e32 v36, v205
	v_mov_b32_e32 v37, v205
	v_mov_b32_e32 v38, v205
	v_mov_b32_e32 v39, v205
	v_mov_b32_e32 v40, v205
	v_mov_b32_e32 v41, v205
	v_mov_b32_e32 v42, v205
	v_mov_b32_e32 v43, v205
	v_mov_b32_e32 v44, v205
	v_mov_b32_e32 v45, v205
	v_mov_b32_e32 v46, v205
	v_mov_b32_e32 v47, v205
	v_mov_b32_e32 v16, v205
	v_mov_b32_e32 v17, v205
	v_mov_b32_e32 v18, v205
	v_mov_b32_e32 v19, v205
	v_mov_b32_e32 v20, v205
	v_mov_b32_e32 v21, v205
	v_mov_b32_e32 v22, v205
	v_mov_b32_e32 v23, v205
	v_mov_b32_e32 v24, v205
	v_mov_b32_e32 v25, v205
	v_mov_b32_e32 v26, v205
	v_mov_b32_e32 v27, v205
	v_mov_b32_e32 v28, v205
	v_mov_b32_e32 v29, v205
	v_mov_b32_e32 v30, v205
	v_mov_b32_e32 v31, v205
	v_mov_b32_e32 v0, v205
	v_mov_b32_e32 v1, v205
	v_mov_b32_e32 v2, v205
	v_mov_b32_e32 v3, v205
	v_mov_b32_e32 v4, v205
	v_mov_b32_e32 v5, v205
	v_mov_b32_e32 v6, v205
	v_mov_b32_e32 v7, v205
	v_mov_b32_e32 v8, v205
	v_mov_b32_e32 v9, v205
	v_mov_b32_e32 v10, v205
	v_mov_b32_e32 v11, v205
	v_mov_b32_e32 v12, v205
	v_mov_b32_e32 v13, v205
	v_mov_b32_e32 v14, v205
	v_mov_b32_e32 v15, v205
.LBB0_1164:
	s_add_i32 s38, s39, 1
	s_cmp_lt_i32 s38, s22
	s_cselect_b64 s[10:11], -1, 0
	s_add_i32 s100, s39, 2
	s_cmp_ge_i32 s100, s22
	s_waitcnt lgkmcnt(0)
	s_barrier
	s_cbranch_scc1 .LBB0_1166
	s_cmp_lt_i32 s100, s19
	s_cselect_b64 s[2:3], -1, 0
	s_and_b64 s[2:3], s[2:3], exec
	s_cselect_b32 s2, 0, s35
	s_cselect_b32 s14, s17, s34
	s_cselect_b32 s15, s16, s33
	s_cselect_b32 s12, s21, s31
	s_cselect_b32 s13, s20, s30
	s_add_i32 s2, s2, s100
	s_ashr_i32 s3, s2, 31
	s_lshl_b64 s[2:3], s[2:3], 13
	s_add_u32 s13, s13, s2
	s_addc_u32 s40, s12, s3
	v_readlane_b32 s74, v254, 6
	v_readlane_b32 s75, v254, 7
	s_add_u32 s12, s13, s74
	s_addc_u32 s13, s40, s75
	s_add_u32 s2, s15, s2
	s_addc_u32 s3, s14, s3
	s_add_u32 s2, s2, s74
	v_lshl_add_u64 v[64:65], s[12:13], 0, v[170:171]
	s_addc_u32 s3, s3, s75
	s_bitcmp1_b32 s39, 0
	s_cbranch_scc1 .Lmy_ldA
	global_load_dwordx4 v[242:245], v[64:65], off
	v_lshl_add_u64 v[64:65], s[2:3], 0, v[170:171]
	global_load_dwordx4 v[246:249], v[64:65], off
	s_branch .LBB0_1166
.Lmy_ldA:
	global_load_dwordx4 v[144:147], v[64:65], off
	v_lshl_add_u64 v[64:65], s[2:3], 0, v[170:171]
	global_load_dwordx4 v[148:151], v[64:65], off

.Lmy_win_fast:
	s_mov_b32 s2, 0x3fb8aa3b
	s_nop 3
	v_pk_fma_f32 v[94:95], v[78:79], s[2:3], v[188:189] op_sel_hi:[1,0,1]
	v_pk_fma_f32 v[92:93], v[76:77], s[2:3], v[186:187] op_sel_hi:[1,0,1]
	v_pk_fma_f32 v[90:91], v[74:75], s[2:3], v[184:185] op_sel_hi:[1,0,1]
	v_pk_fma_f32 v[88:89], v[72:73], s[2:3], v[182:183] op_sel_hi:[1,0,1]
	v_pk_fma_f32 v[86:87], v[70:71], s[2:3], v[180:181] op_sel_hi:[1,0,1]
	v_pk_fma_f32 v[84:85], v[68:69], s[2:3], v[178:179] op_sel_hi:[1,0,1]
	v_pk_fma_f32 v[82:83], v[66:67], s[2:3], v[176:177] op_sel_hi:[1,0,1]
	v_pk_fma_f32 v[80:81], v[64:65], s[2:3], v[172:173] op_sel_hi:[1,0,1]
	v_exp_f32_e32 v96, v80
	v_exp_f32_e32 v97, v81
	v_exp_f32_e32 v98, v82
	v_add_f32_e32 v111, 0, v96
	v_exp_f32_e32 v99, v83
	v_add_f32_e32 v111, v97, v111
	v_exp_f32_e32 v100, v84
	v_add_f32_e32 v111, v98, v111
	v_exp_f32_e32 v101, v85
	v_add_f32_e32 v111, v99, v111
	v_exp_f32_e32 v102, v86
	v_add_f32_e32 v111, v100, v111
	v_exp_f32_e32 v103, v87
	v_add_f32_e32 v111, v101, v111
	v_exp_f32_e32 v104, v88
	v_add_f32_e32 v111, v102, v111
	v_exp_f32_e32 v105, v89
	v_add_f32_e32 v111, v103, v111
	v_exp_f32_e32 v106, v90
	v_add_f32_e32 v111, v104, v111
	v_exp_f32_e32 v107, v91
	v_add_f32_e32 v111, v105, v111
	v_exp_f32_e32 v108, v92
	v_add_f32_e32 v111, v106, v111
	v_exp_f32_e32 v109, v93
	v_add_f32_e32 v111, v107, v111
	v_exp_f32_e32 v110, v94
	v_add_f32_e32 v111, v108, v111
	s_nop 0
	v_add_f32_e32 v111, v109, v111
	s_nop 0
	v_add_f32_e32 v204, v110, v111
	s_mov_b64 s[2:3], -1
	s_branch .LBB0_1186
.LBB0_1174:
	s_and_b32 s12, s23, 0x1000
	v_lshl_add_u32 v155, s12, 1, v152
	ds_read_b128 v[80:83], v155
	ds_read_b128 v[84:87], v155 offset:1024
	ds_read_b128 v[88:91], v155 offset:2048
	ds_read_b128 v[92:95], v155 offset:3072
	ds_read_b128 v[96:99], v155 offset:4096
	ds_read_b128 v[100:103], v155 offset:5120
	ds_read_b128 v[104:107], v155 offset:6144
	ds_read_b128 v[108:111], v155 offset:7168
	s_mov_b64 s[12:13], -1
	s_and_b64 vcc, s[2:3], exec
	s_waitcnt lgkmcnt(7)
	v_mfma_f32_32x32x16_bf16 v[64:79], v[80:83], v[112:115], 0
	s_waitcnt lgkmcnt(6)
	v_mfma_f32_32x32x16_bf16 v[64:79], v[84:87], v[116:119], v[64:79]
	s_waitcnt lgkmcnt(5)
	v_mfma_f32_32x32x16_bf16 v[64:79], v[88:91], v[120:123], v[64:79]
	s_waitcnt lgkmcnt(4)
	v_mfma_f32_32x32x16_bf16 v[64:79], v[92:95], v[124:127], v[64:79]
	s_waitcnt lgkmcnt(3)
	v_mfma_f32_32x32x16_bf16 v[64:79], v[96:99], v[128:131], v[64:79]
	s_waitcnt lgkmcnt(2)
	v_mfma_f32_32x32x16_bf16 v[64:79], v[100:103], v[132:135], v[64:79]
	s_waitcnt lgkmcnt(1)
	v_mfma_f32_32x32x16_bf16 v[64:79], v[104:107], v[136:139], v[64:79]
	s_waitcnt lgkmcnt(0)
	v_mfma_f32_32x32x16_bf16 v[64:79], v[108:111], v[140:143], v[64:79]
	ds_read_b128 v[234:237], v155 offset:16384
	ds_read_b128 v[238:241], v155 offset:17408
	s_cbranch_vccz .LBB0_1180
	s_sub_i32 s2, s27, s40
	s_cmpk_lt_i32 s2, 0x9f
	s_mov_b64 s[2:3], -1
	s_cbranch_scc1 .LBB0_1177
	s_sub_i32 s3, s27, s40
	s_cmpk_gt_i32 s3, 0x1e0
	s_cbranch_scc0 .Lmy_win_fast
	s_mov_b32 s2, 0x3fb8aa3b
	v_add_u32_e32 v111, s40, v166
	s_nop 4
	v_pk_fma_f32 v[94:95], v[78:79], s[2:3], v[188:189] op_sel_hi:[1,0,1]
	v_pk_fma_f32 v[92:93], v[76:77], s[2:3], v[186:187] op_sel_hi:[1,0,1]
	v_pk_fma_f32 v[90:91], v[74:75], s[2:3], v[184:185] op_sel_hi:[1,0,1]
	v_pk_fma_f32 v[88:89], v[72:73], s[2:3], v[182:183] op_sel_hi:[1,0,1]
	v_pk_fma_f32 v[86:87], v[70:71], s[2:3], v[180:181] op_sel_hi:[1,0,1]
	v_pk_fma_f32 v[84:85], v[68:69], s[2:3], v[178:179] op_sel_hi:[1,0,1]
	v_pk_fma_f32 v[82:83], v[66:67], s[2:3], v[176:177] op_sel_hi:[1,0,1]
	v_pk_fma_f32 v[80:81], v[64:65], s[2:3], v[172:173] op_sel_hi:[1,0,1]
	v_sub_u32_e32 v96, v162, v111
	v_xad_u32 v97, v111, -1, v162
	v_sub_u32_e32 v98, v220, v111
	v_sub_u32_e32 v99, v221, v111
	v_sub_u32_e32 v100, v222, v111
	v_sub_u32_e32 v101, v223, v111
	v_sub_u32_e32 v102, v224, v111
	v_sub_u32_e32 v103, v225, v111
	v_sub_u32_e32 v104, v226, v111
	v_sub_u32_e32 v105, v227, v111
	v_sub_u32_e32 v106, v228, v111
	v_sub_u32_e32 v107, v229, v111
	v_sub_u32_e32 v108, v230, v111
	v_sub_u32_e32 v109, v231, v111
	v_sub_u32_e32 v110, v232, v111
	v_sub_u32_e32 v111, v233, v111
	s_mov_b64 s[2:3], 0

.LBB0_1180:
	s_and_b64 vcc, exec, s[12:13]
	s_cbranch_vccz .LBB0_1186
	s_sub_i32 s12, s27, s40
	s_mov_b64 s[2:3], -1
	s_cmpk_lt_i32 s12, 0x9f
	v_add_u32_e32 v96, s40, v166
	s_cbranch_scc1 .LBB0_1183
	s_mov_b32 s2, 0x3fb8aa3b
	s_lshr_b32 s3, s39, 1
	s_nop 1
	v_pk_fma_f32 v[94:95], v[78:79], s[2:3], v[188:189] op_sel_hi:[1,0,1]
	v_pk_fma_f32 v[92:93], v[76:77], s[2:3], v[186:187] op_sel_hi:[1,0,1]
	v_pk_fma_f32 v[90:91], v[74:75], s[2:3], v[184:185] op_sel_hi:[1,0,1]
	v_pk_fma_f32 v[88:89], v[72:73], s[2:3], v[182:183] op_sel_hi:[1,0,1]
	v_pk_fma_f32 v[86:87], v[70:71], s[2:3], v[180:181] op_sel_hi:[1,0,1]
	v_pk_fma_f32 v[84:85], v[68:69], s[2:3], v[178:179] op_sel_hi:[1,0,1]
	v_pk_fma_f32 v[82:83], v[66:67], s[2:3], v[176:177] op_sel_hi:[1,0,1]
	v_pk_fma_f32 v[80:81], v[64:65], s[2:3], v[172:173] op_sel_hi:[1,0,1]
	v_lshrrev_b32_e32 v64, s3, v163
	v_and_b32_e32 v64, 1, v64
	v_cmp_eq_u32_e32 vcc, 1, v64
	v_exp_f32_e32 v65, v80
	v_exp_f32_e32 v66, v81
	v_exp_f32_e32 v67, v82
	v_cndmask_b32_e32 v96, 0, v65, vcc
	v_add_f32_e32 v111, 0, v96
	v_exp_f32_e32 v68, v83
	v_cndmask_b32_e32 v97, 0, v66, vcc
	v_add_f32_e32 v111, v97, v111
	v_exp_f32_e32 v65, v84
	v_cndmask_b32_e32 v98, 0, v67, vcc
	v_add_f32_e32 v111, v98, v111
	v_exp_f32_e32 v66, v85
	v_cndmask_b32_e32 v99, 0, v68, vcc
	v_add_f32_e32 v111, v99, v111
	v_exp_f32_e32 v67, v86
	v_cndmask_b32_e32 v100, 0, v65, vcc
	v_add_f32_e32 v111, v100, v111
	v_exp_f32_e32 v68, v87
	v_cndmask_b32_e32 v101, 0, v66, vcc
	v_add_f32_e32 v111, v101, v111
	v_exp_f32_e32 v65, v88
	v_cndmask_b32_e32 v102, 0, v67, vcc
	v_add_f32_e32 v111, v102, v111
	v_exp_f32_e32 v66, v89
	v_cndmask_b32_e32 v103, 0, v68, vcc
	v_add_f32_e32 v111, v103, v111
	v_exp_f32_e32 v67, v90
	v_cndmask_b32_e32 v104, 0, v65, vcc
	v_add_f32_e32 v111, v104, v111
	v_exp_f32_e32 v68, v91
	v_cndmask_b32_e32 v105, 0, v66, vcc
	v_add_f32_e32 v111, v105, v111
	v_exp_f32_e32 v65, v92
	v_cndmask_b32_e32 v106, 0, v67, vcc
	v_add_f32_e32 v111, v106, v111
	v_exp_f32_e32 v66, v93
	v_cndmask_b32_e32 v107, 0, v68, vcc
	v_add_f32_e32 v111, v107, v111
	v_exp_f32_e32 v67, v94
	v_cndmask_b32_e32 v108, 0, v65, vcc
	v_add_f32_e32 v111, v108, v111
	s_nop 0
	v_cndmask_b32_e32 v109, 0, v66, vcc
	v_add_f32_e32 v111, v109, v111
	s_nop 0
	v_cndmask_b32_e32 v110, 0, v67, vcc
	v_add_f32_e32 v204, v110, v111
	s_mov_b64 s[2:3], vcc
	s_branch .LBB0_1186

.LBB0_1186:
	s_nop 8
	v_exp_f32_e32 v67, v95
	v_cvt_pk_bf16_f32 v64, v96, v97
	v_cvt_pk_bf16_f32 v65, v98, v99
	v_cvt_pk_bf16_f32 v66, v100, v101
	s_nop 0
	v_cndmask_b32_e64 v80, 0, v67, s[2:3]
	v_cvt_pk_bf16_f32 v67, v102, v103
	v_cvt_pk_bf16_f32 v68, v104, v105
	v_cvt_pk_bf16_f32 v69, v106, v107
	v_cvt_pk_bf16_f32 v70, v108, v109
	v_cvt_pk_bf16_f32 v71, v110, v80
	ds_read_b128 v[92:95], v155 offset:18432
	ds_read_b128 v[96:99], v155 offset:19456
	ds_read_b128 v[72:75], v155 offset:20480
	ds_read_b128 v[76:79], v155 offset:21504
	ds_read_b128 v[84:87], v155 offset:22528
	ds_read_b128 v[88:91], v155 offset:23552
	s_waitcnt lgkmcnt(6)
	v_mfma_f32_32x32x16_bf16 v[48:63], v[64:67], v[234:237], v[48:63]
	v_mfma_f32_32x32x16_bf16 v[48:63], v[68:71], v[238:241], v[48:63]
	s_waitcnt lgkmcnt(4)
	v_mfma_f32_32x32x16_bf16 v[32:47], v[64:67], v[92:95], v[32:47]
	v_mfma_f32_32x32x16_bf16 v[32:47], v[68:71], v[96:99], v[32:47]
	s_waitcnt lgkmcnt(2)
	v_mfma_f32_32x32x16_bf16 v[16:31], v[64:67], v[72:75], v[16:31]
	v_mfma_f32_32x32x16_bf16 v[16:31], v[68:71], v[76:79], v[16:31]
	s_waitcnt lgkmcnt(0)
	v_mfma_f32_32x32x16_bf16 v[0:15], v[64:67], v[84:87], v[0:15]
	v_add_f32_e32 v64, v80, v204
	v_add_f32_e32 v205, v205, v64
	v_mfma_f32_32x32x16_bf16 v[0:15], v[68:71], v[88:91], v[0:15]
	s_cmp_lg_u32 s18, s39
	s_cbranch_scc1 .LBB0_1172

.LBB0_1190:
	s_addk_i32 s23, 0x1000
	s_and_b32 s2, s23, 0x1000
	v_lshl_add_u32 v64, s2, 1, v219
	s_add_i32 s100, s39, 2
	s_cmp_lt_i32 s100, s22
	s_cbranch_scc1 .Lmy_w2
	s_waitcnt vmcnt(0)
	s_branch .Lmy_w3
.Lmy_w2:
	s_waitcnt vmcnt(2)
.Lmy_w3:
	s_bitcmp1_b32 s39, 0
	s_cbranch_scc1 .Lmy_wrB
	ds_write_b128 v64, v[144:147]
	ds_write_b128 v64, v[148:151] offset:16384
	s_branch .LBB0_1191
.Lmy_wrB:
	ds_write_b128 v64, v[242:245]
	ds_write_b128 v64, v[246:249] offset:16384
